# Resid main phase's last K-iteration prefetches the tail half-unit's K-tiles 0/1 (instead of dummy re-reads); tail prologue staging loads removed
# speedup vs baseline: 1.0080x; 1.0080x over previous
.LBB0_666:
	s_nop 0
	v_cndmask_b32_e64 v2, 0, 1, s[6:7]
	v_cmp_ne_u32_e64 s[4:5], 1, v2
	s_andn2_b64 vcc, exec, s[6:7]
	v_readlane_b32 s0, v254, 27
	s_lshr_b32 s6, s60, 1
	s_mul_i32 s0, s6, s0
	s_add_u32 s50, s40, s0
	s_addc_u32 s51, s41, 0
	s_cbranch_vccnz .LBB0_668
	s_mul_i32 s6, s87, s60
	s_mul_hi_i32 s0, s87, s60
	s_add_u32 s50, s40, s6
	s_addc_u32 s51, s41, s0
.LBB0_668:
	s_and_b64 vcc, exec, s[4:5]
	v_readlane_b32 s0, v254, 28
	s_mul_hi_i32 s6, s60, s0
	s_mul_i32 s0, s60, s0
	s_add_u32 s52, s44, s0
	s_addc_u32 s53, s45, s6
	s_cbranch_vccnz .LBB0_670
	s_mul_i32 s6, s13, s60
	s_mul_hi_i32 s0, s13, s60
	s_add_u32 s52, s44, s6
	s_addc_u32 s53, s45, s0

.LBB0_782:
	v_readlane_b32 s4, v254, 2
	v_readlane_b32 s5, v254, 3
	s_andn2_b64 vcc, exec, s[4:5]
	s_cbranch_vccnz .LBB0_847
	v_readlane_b32 s4, v254, 25
	v_mov_b32_e32 v5, v220
	v_readlane_b32 s5, v254, 26
	s_andn2_b64 vcc, exec, s[4:5]
	v_readfirstlane_b32 s3, v5
	s_cbranch_vccnz .LBB0_847
	v_lshlrev_b32_e32 v1, 4, v5
	v_add_u32_e32 v2, 0x2000, v1
	s_waitcnt lgkmcnt(0)
	v_ashrrev_i32_e32 v3, 31, v2
	v_lshrrev_b32_e32 v3, 22, v3
	v_add_u32_e32 v3, v2, v3
	v_ashrrev_i32_e32 v3, 10, v3
	v_mul_i32_i24_e32 v4, 0x400, v3
	v_sub_u32_e32 v2, v2, v4
	v_lshrrev_b32_e32 v4, 4, v2
	v_bitop3_b32 v4, v4, v2, 32 bitop3:0x6c
	v_ashrrev_i32_e32 v2, 31, v4
	v_lshrrev_b32_e32 v2, 26, v2
	v_add_u32_e32 v6, v4, v2
	v_lshlrev_b32_e32 v7, 3, v3
	v_ashrrev_i32_e32 v2, 6, v6
	v_and_b32_e32 v7, -16, v7
	v_add_u32_e32 v7, v2, v7
	v_and_b32_e32 v2, 3, v2
	s_mov_b32 s4, 0x7fffffe0
	v_lshrrev_b32_e32 v8, 2, v7
	v_lshlrev_b32_e32 v9, 1, v7
	v_and_or_b32 v2, v7, s4, v2
	v_and_b32_e32 v8, 4, v8
	v_and_b32_e32 v9, 24, v9
	v_or3_b32 v2, v2, v8, v9
	v_mul_lo_u32 v8, v2, s1
	v_lshlrev_b32_e32 v2, 5, v3
	v_and_b32_e32 v3, 0xc0, v6
	v_sub_u32_e32 v3, v4, v3
	v_ashrrev_i16_sdwa v3, v235, sext(v3) dst_sel:DWORD dst_unused:UNUSED_PAD src0_sel:DWORD src1_sel:BYTE_0
	v_and_b32_e32 v2, 32, v2
	v_bfe_i32 v3, v3, 0, 16
	v_add_u32_e32 v6, v2, v3
	v_mul_lo_u32 v4, v7, s1
	v_add_lshl_u32 v34, v8, v6, 1
	v_add_lshl_u32 v36, v6, v4, 1
	v_bfe_i32 v6, v5, 27, 1
	v_lshrrev_b32_e32 v6, 22, v6
	v_add_u32_e32 v6, v1, v6
	v_and_b32_e32 v6, 0xfffffc00, v6
	v_sub_u32_e32 v1, v1, v6
	v_lshrrev_b32_e32 v6, 4, v1
	v_ashrrev_i32_e32 v8, 31, v5
	v_bitop3_b32 v1, v6, v1, 32 bitop3:0x6c
	v_lshrrev_b32_e32 v8, 26, v8
	v_ashrrev_i32_e32 v6, 31, v1
	v_add_u32_e32 v8, v5, v8
	v_lshrrev_b32_e32 v6, 26, v6
	v_ashrrev_i32_e32 v8, 6, v8
	v_add_u32_e32 v7, v1, v6
	v_lshlrev_b32_e32 v9, 3, v8
	v_ashrrev_i32_e32 v6, 6, v7
	v_and_b32_e32 v9, -16, v9
	v_add_u32_e32 v9, v6, v9
	v_and_b32_e32 v6, 3, v6
	v_lshrrev_b32_e32 v10, 2, v9
	v_lshlrev_b32_e32 v11, 1, v9
	s_lshr_b32 s0, s60, 1
	v_and_or_b32 v6, v9, s4, v6
	v_and_b32_e32 v10, 4, v10
	v_and_b32_e32 v11, 24, v11
	v_and_b32_e32 v7, 0xc0, v7
	v_readlane_b32 s4, v254, 27
	s_ashr_i32 s14, s3, 6
	v_or3_b32 v6, v6, v10, v11
	v_sub_u32_e32 v1, v1, v7
	s_mul_i32 s0, s0, s4
	v_readlane_b32 s4, v254, 28
	s_ashr_i32 s15, s3, 8
	s_lshl_b32 s13, s14, 10
	v_mul_lo_u32 v10, v6, s1
	v_lshlrev_b32_e32 v6, 5, v8
	v_ashrrev_i16_sdwa v1, v235, sext(v1) dst_sel:DWORD dst_unused:UNUSED_PAD src0_sel:DWORD src1_sel:BYTE_0
	s_mul_hi_i32 s5, s60, s4
	s_mul_i32 s60, s60, s4
	v_and_b32_e32 v6, 32, v6
	v_bfe_i32 v7, v1, 0, 16
	s_add_u32 s4, s44, s60
	v_add_u32_e32 v1, v6, v7
	s_addc_u32 s5, s45, s5
	s_add_i32 s20, s13, 0
	v_add_lshl_u32 v38, v10, v1, 1
	s_add_i32 m0, s20, 0x10000
	v_mul_lo_u32 v8, v9, s1
	s_add_i32 m0, s20, 0x12000
	s_add_u32 s8, s4, s12
	s_addc_u32 s9, s5, 0
	s_add_i32 m0, s20, 0x14000
	v_add_lshl_u32 v40, v1, v8, 1
	s_add_i32 m0, s20, 0x16000
	s_add_u32 s6, s40, s0
	s_addc_u32 s7, s41, 0
	s_mov_b32 m0, s20
	s_add_i32 s26, s20, 0x2000
	s_mov_b32 m0, s26
	s_add_i32 s27, s20, 0x4000
	s_mov_b32 m0, s27
	s_add_i32 s30, s20, 0x6000
	s_mov_b32 m0, s30
	s_cmp_lg_u32 s15, 1
	s_cbranch_scc1 .LBB0_786
	s_barrier
.LBB0_786:
	v_mov_b32_e32 v39, v0
	v_lshl_add_u64 v[10:11], s[4:5], 0, v[38:39]
	v_mov_b32_e32 v35, v0
	v_lshl_add_u64 v[12:13], s[4:5], 0, v[34:35]
	v_mov_b32_e32 v41, v0
	s_add_i32 m0, s20, 0x18000
	v_lshl_add_u64 v[10:11], v[10:11], 0, s[76:77]
	v_lshl_add_u64 v[18:19], s[6:7], 0, v[40:41]
	v_mov_b32_e32 v37, v0
	s_waitcnt vmcnt(2)
	s_barrier
	v_lshl_add_u64 v[10:11], v[12:13], 0, s[76:77]
	s_add_i32 m0, s20, 0x1a000
	s_add_i32 s31, s20, 0x8000
	v_lshl_add_u64 v[20:21], s[6:7], 0, v[36:37]
	v_lshl_add_u64 v[10:11], v[18:19], 0, s[76:77]
	s_mov_b32 m0, s31
	s_add_i32 s34, s20, 0xa000
	v_lshl_add_u64 v[14:15], s[8:9], 0, v[38:39]
	v_lshl_add_u64 v[10:11], v[20:21], 0, s[76:77]
	s_mov_b32 m0, s34
	v_lshl_add_u64 v[16:17], s[8:9], 0, v[34:35]
	s_add_i32 m0, s20, 0x1c000
	v_lshl_add_u64 v[10:11], v[14:15], 0, s[76:77]
	v_lshl_add_u64 v[10:11], v[16:17], 0, s[76:77]
	s_add_i32 m0, s20, 0x1e000
	v_bfe_u32 v1, v5, 4, 2
	v_and_b32_e32 v9, 15, v5
	v_lshlrev_b32_e32 v22, 4, v1
	v_lshlrev_b32_e32 v5, 2, v5
	v_lshl_or_b32 v114, s15, 6, v9
	v_lshl_or_b32 v9, v9, 6, v22
	s_lshl_b32 s0, s15, 13
	v_and_b32_e32 v5, 32, v5
	v_bitop3_b32 v22, v9, s0, v5 bitop3:0xde
	s_lshl_b32 s0, s14, 5
	s_and_b32 s21, s0, 0x60
	s_lshl_b32 s0, s21, 7
	v_bitop3_b32 v54, v9, s0, v5 bitop3:0xde
	v_readlane_b32 s0, v254, 56
	s_add_i32 s35, s36, -2
	s_mul_i32 s0, s0, s1
	s_add_u32 s0, s10, s0
	s_addc_u32 s1, s11, 0
	s_add_u32 s0, s38, s0
	s_addc_u32 s1, s37, s1
	s_add_u32 s8, s0, 0x80
	v_add_u32_e32 v2, v4, v2
	s_waitcnt vmcnt(6)
	v_add_u32_e32 v5, v8, v6
	s_addc_u32 s9, s1, 0
	v_add_lshl_u32 v2, v2, v3, 1
	v_mov_b32_e32 v3, v0
	v_add_lshl_u32 v6, v5, v7, 1
	v_mov_b32_e32 v7, v0
	v_lshl_add_u64 v[52:53], s[8:9], 0, v[2:3]
	v_lshl_add_u64 v[50:51], s[8:9], 0, v[6:7]
	s_mov_b32 s14, 0
	s_mov_b64 s[8:9], 0
	v_add_u32_e32 v55, 0, v22
	s_barrier
	s_movk_i32 s8, 0x100
	s_lshl_b32 s9, s36, 7
	s_mov_b32 s14, 0
	v_add_u32_e32 v68, 0x10000, v54
	v_add_u32_e32 v69, 0x21c00, v54
	s_add_u32 s40, s4, s8
	s_addc_u32 s41, s5, 0
	s_add_u32 s42, s40, s12
	s_addc_u32 s43, s41, 0
	s_add_u32 s10, s6, s8
	s_addc_u32 s11, s7, 0
	s_addk_i32 s8, 0x80
	s_cmp_eq_u32 s8, s9
	s_cselect_b32 s8, 0, s8
	s_add_i32 m0, s20, 0xc000
	ds_read_b128 v[56:59], v68 offset:0
	ds_read_b128 v[60:63], v68 offset:1024
	ds_read_b128 v[64:67], v68 offset:2048
	ds_read_b128 v[74:77], v68 offset:3072
	global_load_lds_dwordx4 v38, s[40:41]
	s_add_i32 m0, s20, 0xe000
	ds_read_b128 v[116:119], v55 offset:0
	ds_read_b128 v[120:123], v55 offset:1024
	ds_read_b128 v[124:127], v55 offset:2048
	global_load_lds_dwordx4 v34, s[40:41]
	s_add_i32 m0, s20, 0x21c00
	ds_read_b128 v[128:131], v55 offset:3072
	ds_read_b128 v[132:135], v55 offset:4096
	ds_read_b128 v[136:139], v55 offset:5120
	global_load_lds_dwordx4 v38, s[42:43]
	s_add_i32 m0, s20, 0x23c00
	ds_read_b128 v[140:143], v55 offset:6144
	ds_read_b128 v[144:147], v55 offset:7168
	global_load_lds_dwordx4 v34, s[42:43]
	s_add_i32 m0, s20, 0x4000
	ds_read_b128 v[98:101], v68 offset:16384
	ds_read_b128 v[102:105], v68 offset:17408
	global_load_lds_dwordx4 v40, s[10:11]
	s_add_i32 m0, s20, 0x6000
	ds_read_b128 v[106:109], v68 offset:18432
	ds_read_b128 v[110:113], v68 offset:19456
	global_load_lds_dwordx4 v36, s[10:11]
	s_waitcnt vmcnt(6)
	s_waitcnt lgkmcnt(0)
	s_barrier
	s_setprio 1
	v_mfma_f32_16x16x32_bf16 v[94:97], v[56:59], v[116:119], 0
	v_mfma_f32_16x16x32_bf16 v[90:93], v[64:67], v[116:119], 0
	v_mfma_f32_16x16x32_bf16 v[78:81], v[56:59], v[124:127], 0
	s_add_u32 s40, s4, s8
	v_mfma_f32_16x16x32_bf16 v[70:73], v[64:67], v[124:127], 0
	s_addc_u32 s41, s5, 0
	v_mfma_f32_16x16x32_bf16 v[30:33], v[56:59], v[132:135], 0
	s_add_u32 s42, s40, s12
	v_mfma_f32_16x16x32_bf16 v[26:29], v[64:67], v[132:135], 0
	s_addc_u32 s43, s41, 0
	v_mfma_f32_16x16x32_bf16 v[14:17], v[56:59], v[140:143], 0
	s_add_u32 s10, s6, s8
	v_mfma_f32_16x16x32_bf16 v[10:13], v[64:67], v[140:143], 0
	s_addc_u32 s11, s7, 0
	v_mfma_f32_16x16x32_bf16 v[94:97], v[60:63], v[120:123], v[94:97]
	s_addk_i32 s8, 0x80
	v_mfma_f32_16x16x32_bf16 v[90:93], v[74:77], v[120:123], v[90:93]
	s_cmp_eq_u32 s8, s9
	v_mfma_f32_16x16x32_bf16 v[78:81], v[60:63], v[128:131], v[78:81]
	s_cselect_b32 s8, 0, s8
	v_mfma_f32_16x16x32_bf16 v[70:73], v[74:77], v[128:131], v[70:73]
	v_mfma_f32_16x16x32_bf16 v[30:33], v[60:63], v[136:139], v[30:33]
	v_mfma_f32_16x16x32_bf16 v[26:29], v[74:77], v[136:139], v[26:29]
	v_mfma_f32_16x16x32_bf16 v[14:17], v[60:63], v[144:147], v[14:17]
	v_mfma_f32_16x16x32_bf16 v[10:13], v[74:77], v[144:147], v[10:13]
	v_mfma_f32_16x16x32_bf16 v[86:89], v[98:101], v[116:119], 0
	v_mfma_f32_16x16x32_bf16 v[82:85], v[106:109], v[116:119], 0
	v_mfma_f32_16x16x32_bf16 v[46:49], v[98:101], v[124:127], 0
	v_mfma_f32_16x16x32_bf16 v[42:45], v[106:109], v[124:127], 0
	v_mfma_f32_16x16x32_bf16 v[22:25], v[98:101], v[132:135], 0
	v_mfma_f32_16x16x32_bf16 v[18:21], v[106:109], v[132:135], 0
	v_mfma_f32_16x16x32_bf16 v[6:9], v[98:101], v[140:143], 0
	v_mfma_f32_16x16x32_bf16 v[2:5], v[106:109], v[140:143], 0
	v_mfma_f32_16x16x32_bf16 v[86:89], v[102:105], v[120:123], v[86:89]
	v_mfma_f32_16x16x32_bf16 v[82:85], v[110:113], v[120:123], v[82:85]
	v_mfma_f32_16x16x32_bf16 v[46:49], v[102:105], v[128:131], v[46:49]
	v_mfma_f32_16x16x32_bf16 v[42:45], v[110:113], v[128:131], v[42:45]
	v_mfma_f32_16x16x32_bf16 v[22:25], v[102:105], v[136:139], v[22:25]
	v_mfma_f32_16x16x32_bf16 v[18:21], v[110:113], v[136:139], v[18:21]
	v_mfma_f32_16x16x32_bf16 v[6:9], v[102:105], v[144:147], v[6:9]
	v_mfma_f32_16x16x32_bf16 v[2:5], v[110:113], v[144:147], v[2:5]
	s_setprio 0
	s_barrier
	s_add_i32 s14, s14, 1
